# scan loop v3 (2-deep prefetch ring, gelu of previous tile behind MFMAs, single C*h accumulator), attention epilogue gate loads hoisted, first-step LDS pipelining
# speedup vs baseline: 1.0128x; 1.0029x over previous
.LBB0_225:
	s_add_i32 s82, s82, s76
	v_or_b32_e32 v0, s82, v183
	v_lshlrev_b32_e32 v2, 3, v0
	v_and_b32_e32 v14, 0xffffff80, v2
	v_or_b32_e32 v112, s78, v14
	v_ashrrev_i32_e32 v113, 31, v112
	v_lshlrev_b64 v[112:113], 10, v[112:113]
	v_lshl_add_u64 v[112:113], v[172:173], 0, v[112:113]
	global_load_dwordx2 v[114:115], v[112:113], off
	global_load_dwordx2 v[116:117], v[112:113], off offset:16
	global_load_dwordx2 v[118:119], v[112:113], off offset:32
	global_load_dwordx2 v[120:121], v[112:113], off offset:48
	v_or_b32_e32 v110, s79, v14
	v_ashrrev_i32_e32 v111, 31, v110
	v_lshlrev_b64 v[110:111], 10, v[110:111]
	v_lshl_add_u64 v[110:111], v[172:173], 0, v[110:111]
	global_load_dwordx2 v[122:123], v[110:111], off
	global_load_dwordx2 v[124:125], v[110:111], off offset:16
	global_load_dwordx2 v[126:127], v[110:111], off offset:32
	global_load_dwordx2 v[128:129], v[110:111], off offset:48
	v_or_b32_e32 v112, v14, v210
	v_ashrrev_i32_e32 v113, 31, v112
	v_lshlrev_b64 v[112:113], 10, v[112:113]
	v_lshl_add_u64 v[112:113], v[172:173], 0, v[112:113]
	global_load_dwordx2 v[130:131], v[112:113], off
	v_or_b32_e32 v110, v14, v212
	v_ashrrev_i32_e32 v111, 31, v110
	v_lshlrev_b64 v[110:111], 10, v[110:111]
	v_lshl_add_u64 v[110:111], v[172:173], 0, v[110:111]
	global_load_dwordx2 v[132:133], v[110:111], off offset:16
	v_or_b32_e32 v112, v14, v214
	v_ashrrev_i32_e32 v113, 31, v112
	v_lshlrev_b64 v[112:113], 10, v[112:113]
	v_lshl_add_u64 v[112:113], v[172:173], 0, v[112:113]
	global_load_dwordx2 v[134:135], v[112:113], off offset:32
	v_or_b32_e32 v110, v14, v216
	v_ashrrev_i32_e32 v111, 31, v110
	v_lshlrev_b64 v[110:111], 10, v[110:111]
	v_lshl_add_u64 v[110:111], v[172:173], 0, v[110:111]
	global_load_dwordx2 v[136:137], v[110:111], off offset:48
	v_or_b32_e32 v112, v14, v209
	v_ashrrev_i32_e32 v113, 31, v112
	v_lshlrev_b64 v[112:113], 10, v[112:113]
	v_lshl_add_u64 v[112:113], v[172:173], 0, v[112:113]
	global_load_dwordx2 v[138:139], v[112:113], off
	v_or_b32_e32 v110, v14, v219
	v_ashrrev_i32_e32 v111, 31, v110
	v_lshlrev_b64 v[110:111], 10, v[110:111]
	v_lshl_add_u64 v[110:111], v[172:173], 0, v[110:111]
	global_load_dwordx2 v[140:141], v[110:111], off offset:16
	v_or_b32_e32 v112, v14, v221
	v_ashrrev_i32_e32 v113, 31, v112
	v_lshlrev_b64 v[112:113], 10, v[112:113]
	v_lshl_add_u64 v[112:113], v[172:173], 0, v[112:113]
	global_load_dwordx2 v[142:143], v[112:113], off offset:32
	v_or_b32_e32 v110, v14, v223
	v_ashrrev_i32_e32 v111, 31, v110
	v_lshlrev_b64 v[110:111], 10, v[110:111]
	v_lshl_add_u64 v[110:111], v[172:173], 0, v[110:111]
	global_load_dwordx2 v[144:145], v[110:111], off offset:48
	v_lshlrev_b32_e32 v2, 5, v0
	v_and_b32_e32 v8, 0x1e0, v2
	v_lshlrev_b32_e32 v2, 1, v0
	v_and_b32_e32 v9, 16, v2
	v_or_b32_e32 v2, s78, v14
	v_ashrrev_i32_e32 v3, 31, v2
	v_lshlrev_b64 v[2:3], 10, v[2:3]
	v_lshl_add_u64 v[4:5], v[172:173], 0, v[2:3]
	v_lshlrev_b32_e32 v0, 6, v0
	s_ashr_i32 s2, s82, 2
	v_and_b32_e32 v0, 0x1c00, v0
	v_readlane_b32 s0, v250, 38
	s_andn2_b32 s2, s2, 63
	v_or3_b32 v10, v9, v8, v189
	v_or_b32_e32 v15, s0, v0
	s_or_b32 s0, s2, s80
	s_ashr_i32 s1, s0, 31
	s_lshl_b64 s[0:1], s[0:1], 15
	s_add_u32 s0, s50, s0
	s_addc_u32 s1, s51, s1
	v_mov_b32_e32 v13, v1
	v_mov_b32_e32 v11, v1
	s_add_i32 s81, s81, 1
	s_cmp_eq_u32 s81, 4
	s_waitcnt vmcnt(15)
	v_lshlrev_b32_e32 v0, 16, v114
	v_and_b32_e32 v2, 0xffff0000, v114
	v_mul_f32_e32 v0, v80, v0
	v_mul_f32_e32 v2, v81, v2
	v_cvt_pk_bf16_f32 v2, v0, v2
	v_lshlrev_b32_e32 v0, 16, v115
	v_and_b32_e32 v3, 0xffff0000, v115
	v_mul_f32_e32 v0, v82, v0
	v_mul_f32_e32 v3, v83, v3
	v_cvt_pk_bf16_f32 v3, v0, v3
	v_or_b32_e32 v0, v10, v15
	v_lshlrev_b32_e32 v0, 1, v0
	global_store_dwordx2 v0, v[2:3], s[0:1]
	v_bitop3_b32 v80, v8, v9, v198 bitop3:0x36
	v_bitop3_b32 v81, v8, v9, v199 bitop3:0x36
	v_mov_b32_e32 v9, v1
	s_waitcnt vmcnt(15)
	v_lshlrev_b32_e32 v6, 16, v116
	v_and_b32_e32 v2, 0xffff0000, v116
	v_mul_f32_e32 v6, v84, v6
	v_mul_f32_e32 v2, v85, v2
	v_cvt_pk_bf16_f32 v6, v6, v2
	v_lshlrev_b32_e32 v2, 16, v117
	v_mul_f32_e32 v2, v86, v2
	v_and_b32_e32 v3, 0xffff0000, v117
	v_mul_f32_e32 v3, v87, v3
	v_cvt_pk_bf16_f32 v7, v2, v3
	v_add_lshl_u32 v2, v10, v15, 1
	global_store_dwordx2 v2, v[6:7], s[0:1] offset:16
	s_waitcnt vmcnt(15)
	v_lshlrev_b32_e32 v3, 16, v118
	v_and_b32_e32 v6, 0xffff0000, v118
	v_mul_f32_e32 v3, v88, v3
	v_mul_f32_e32 v6, v89, v6
	v_cvt_pk_bf16_f32 v6, v3, v6
	v_lshlrev_b32_e32 v3, 16, v119
	v_and_b32_e32 v7, 0xffff0000, v119
	v_mul_f32_e32 v3, v90, v3
	v_mul_f32_e32 v7, v91, v7
	v_cvt_pk_bf16_f32 v7, v3, v7
	v_or_b32_e32 v3, v80, v15
	v_lshlrev_b32_e32 v12, 1, v3
	global_store_dwordx2 v12, v[6:7], s[0:1]
	s_waitcnt vmcnt(15)
	v_lshlrev_b32_e32 v3, 16, v120
	v_and_b32_e32 v4, 0xffff0000, v120
	v_mul_f32_e32 v3, v92, v3
	v_mul_f32_e32 v4, v93, v4
	v_cvt_pk_bf16_f32 v4, v3, v4
	v_lshlrev_b32_e32 v3, 16, v121
	v_and_b32_e32 v5, 0xffff0000, v121
	v_mul_f32_e32 v3, v94, v3
	v_mul_f32_e32 v5, v95, v5
	v_cvt_pk_bf16_f32 v5, v3, v5
	v_or_b32_e32 v3, v81, v15
	v_lshlrev_b32_e32 v10, 1, v3
	global_store_dwordx2 v10, v[4:5], s[0:1]
	v_or_b32_e32 v4, s79, v14
	v_ashrrev_i32_e32 v5, 31, v4
	v_lshlrev_b64 v[4:5], 10, v[4:5]
	v_lshl_add_u64 v[4:5], v[172:173], 0, v[4:5]
	s_waitcnt vmcnt(15)
	v_lshlrev_b32_e32 v3, 16, v122
	v_and_b32_e32 v6, 0xffff0000, v122
	v_mul_f32_e32 v3, v64, v3
	v_mul_f32_e32 v6, v65, v6
	v_cvt_pk_bf16_f32 v6, v3, v6
	v_lshlrev_b32_e32 v3, 16, v123
	v_and_b32_e32 v7, 0xffff0000, v123
	v_mul_f32_e32 v7, v67, v7
	v_mul_f32_e32 v3, v66, v3
	v_cvt_pk_bf16_f32 v7, v3, v7
	global_store_dwordx2 v2, v[6:7], s[0:1] offset:1024
	v_mov_b32_e32 v3, v1
	s_waitcnt vmcnt(15)
	v_lshlrev_b32_e32 v8, 16, v124
	v_and_b32_e32 v6, 0xffff0000, v124
	v_mul_f32_e32 v8, v68, v8
	v_mul_f32_e32 v6, v69, v6
	v_cvt_pk_bf16_f32 v6, v8, v6
	v_lshlrev_b32_e32 v8, 16, v125
	v_and_b32_e32 v7, 0xffff0000, v125
	v_mul_f32_e32 v8, v70, v8
	v_mul_f32_e32 v7, v71, v7
	v_cvt_pk_bf16_f32 v7, v8, v7
	v_add_u32_e32 v8, 0x400, v2
	global_store_dwordx2 v8, v[6:7], s[0:1] offset:16
	s_waitcnt vmcnt(15)
	v_lshlrev_b32_e32 v64, 16, v126
	v_and_b32_e32 v6, 0xffff0000, v126
	v_mul_f32_e32 v64, v72, v64
	v_mul_f32_e32 v6, v73, v6
	v_cvt_pk_bf16_f32 v64, v64, v6
	v_lshlrev_b32_e32 v6, 16, v127
	v_mul_f32_e32 v6, v74, v6
	v_and_b32_e32 v7, 0xffff0000, v127
	v_mul_f32_e32 v7, v75, v7
	v_cvt_pk_bf16_f32 v65, v6, v7
	v_add_lshl_u32 v6, v80, v15, 1
	global_store_dwordx2 v6, v[64:65], s[0:1] offset:1024
	v_mov_b32_e32 v7, v1
	s_waitcnt vmcnt(15)
	v_lshlrev_b32_e32 v64, 16, v128
	v_and_b32_e32 v4, 0xffff0000, v128
	v_mul_f32_e32 v64, v76, v64
	v_mul_f32_e32 v4, v77, v4
	v_cvt_pk_bf16_f32 v64, v64, v4
	v_lshlrev_b32_e32 v4, 16, v129
	v_mul_f32_e32 v4, v78, v4
	v_and_b32_e32 v5, 0xffff0000, v129
	v_mul_f32_e32 v5, v79, v5
	v_cvt_pk_bf16_f32 v65, v4, v5
	v_add_lshl_u32 v4, v81, v15, 1
	global_store_dwordx2 v4, v[64:65], s[0:1] offset:1024
	v_or_b32_e32 v64, v14, v210
	v_ashrrev_i32_e32 v65, 31, v64
	v_lshlrev_b64 v[64:65], 10, v[64:65]
	v_lshl_add_u64 v[64:65], v[172:173], 0, v[64:65]
	v_mov_b32_e32 v5, v1
	s_waitcnt vmcnt(15)
	v_lshlrev_b32_e32 v15, 16, v130
	v_mul_f32_e32 v15, v48, v15
	v_and_b32_e32 v48, 0xffff0000, v130
	v_mul_f32_e32 v48, v49, v48
	v_cvt_pk_bf16_f32 v48, v15, v48
	v_lshlrev_b32_e32 v15, 16, v131
	v_mul_f32_e32 v15, v50, v15
	v_and_b32_e32 v49, 0xffff0000, v131
	v_or_b32_e32 v50, s2, v211
	v_mul_f32_e32 v49, v51, v49
	v_ashrrev_i32_e32 v51, 31, v50
	v_lshlrev_b64 v[50:51], 15, v[50:51]
	v_lshl_add_u64 v[50:51], s[50:51], 0, v[50:51]
	v_lshl_add_u64 v[50:51], v[50:51], 0, v[0:1]
	v_cvt_pk_bf16_f32 v49, v15, v49
	global_store_dwordx2 v[50:51], v[48:49], off
	v_or_b32_e32 v48, v14, v212
	v_ashrrev_i32_e32 v49, 31, v48
	v_lshlrev_b64 v[48:49], 10, v[48:49]
	v_lshl_add_u64 v[48:49], v[172:173], 0, v[48:49]
	v_or_b32_e32 v50, s2, v213
	v_ashrrev_i32_e32 v51, 31, v50
	v_lshlrev_b64 v[50:51], 15, v[50:51]
	v_lshl_add_u64 v[50:51], s[50:51], 0, v[50:51]
	v_lshl_add_u64 v[50:51], v[50:51], 0, v[2:3]
	s_waitcnt vmcnt(15)
	v_lshlrev_b32_e32 v0, 16, v132
	v_and_b32_e32 v15, 0xffff0000, v132
	v_mul_f32_e32 v0, v52, v0
	v_mul_f32_e32 v15, v53, v15
	v_cvt_pk_bf16_f32 v48, v0, v15
	v_lshlrev_b32_e32 v0, 16, v133
	v_and_b32_e32 v15, 0xffff0000, v133
	v_mul_f32_e32 v0, v54, v0
	v_mul_f32_e32 v15, v55, v15
	v_cvt_pk_bf16_f32 v49, v0, v15
	global_store_dwordx2 v[50:51], v[48:49], off offset:16
	v_or_b32_e32 v48, v14, v214
	v_ashrrev_i32_e32 v49, 31, v48
	v_lshlrev_b64 v[48:49], 10, v[48:49]
	v_lshl_add_u64 v[48:49], v[172:173], 0, v[48:49]
	v_or_b32_e32 v50, s2, v215
	v_ashrrev_i32_e32 v51, 31, v50
	v_lshlrev_b64 v[50:51], 15, v[50:51]
	v_lshl_add_u64 v[50:51], s[50:51], 0, v[50:51]
	v_lshl_add_u64 v[12:13], v[50:51], 0, v[12:13]
	s_waitcnt vmcnt(15)
	v_lshlrev_b32_e32 v0, 16, v134
	v_and_b32_e32 v15, 0xffff0000, v134
	v_mul_f32_e32 v0, v56, v0
	v_mul_f32_e32 v15, v57, v15
	v_cvt_pk_bf16_f32 v48, v0, v15
	v_lshlrev_b32_e32 v0, 16, v135
	v_and_b32_e32 v15, 0xffff0000, v135
	v_mul_f32_e32 v0, v58, v0
	v_mul_f32_e32 v15, v59, v15
	v_cvt_pk_bf16_f32 v49, v0, v15
	global_store_dwordx2 v[12:13], v[48:49], off
	v_or_b32_e32 v12, v14, v216
	v_ashrrev_i32_e32 v13, 31, v12
	v_lshlrev_b64 v[12:13], 10, v[12:13]
	v_lshl_add_u64 v[12:13], v[172:173], 0, v[12:13]
	v_or_b32_e32 v48, s2, v217
	v_ashrrev_i32_e32 v49, 31, v48
	v_lshlrev_b64 v[48:49], 15, v[48:49]
	v_lshl_add_u64 v[48:49], s[50:51], 0, v[48:49]
	v_lshl_add_u64 v[10:11], v[48:49], 0, v[10:11]
	s_waitcnt vmcnt(15)
	v_lshlrev_b32_e32 v0, 16, v136
	v_and_b32_e32 v12, 0xffff0000, v136
	v_mul_f32_e32 v0, v60, v0
	v_mul_f32_e32 v12, v61, v12
	v_cvt_pk_bf16_f32 v12, v0, v12
	v_lshlrev_b32_e32 v0, 16, v137
	v_and_b32_e32 v13, 0xffff0000, v137
	v_mul_f32_e32 v13, v63, v13
	v_mul_f32_e32 v0, v62, v0
	v_cvt_pk_bf16_f32 v13, v0, v13
	global_store_dwordx2 v[10:11], v[12:13], off
	v_or_b32_e32 v10, v14, v209
	v_ashrrev_i32_e32 v11, 31, v10
	v_lshlrev_b64 v[10:11], 10, v[10:11]
	v_lshl_add_u64 v[10:11], v[172:173], 0, v[10:11]
	v_or_b32_e32 v12, s2, v218
	v_ashrrev_i32_e32 v13, 31, v12
	v_lshlrev_b64 v[12:13], 15, v[12:13]
	v_lshl_add_u64 v[12:13], s[50:51], 0, v[12:13]
	v_lshl_add_u64 v[2:3], v[12:13], 0, v[2:3]
	s_waitcnt vmcnt(15)
	v_lshlrev_b32_e32 v0, 16, v138
	v_and_b32_e32 v10, 0xffff0000, v138
	v_mul_f32_e32 v0, v32, v0
	v_mul_f32_e32 v10, v33, v10
	v_cvt_pk_bf16_f32 v10, v0, v10
	v_lshlrev_b32_e32 v0, 16, v139
	v_and_b32_e32 v11, 0xffff0000, v139
	v_mul_f32_e32 v11, v35, v11
	v_mul_f32_e32 v0, v34, v0
	v_cvt_pk_bf16_f32 v11, v0, v11
	global_store_dwordx2 v[2:3], v[10:11], off offset:1024
	v_or_b32_e32 v2, v14, v219
	v_ashrrev_i32_e32 v3, 31, v2
	v_lshlrev_b64 v[2:3], 10, v[2:3]
	v_lshl_add_u64 v[2:3], v[172:173], 0, v[2:3]
	v_or_b32_e32 v10, s2, v220
	v_ashrrev_i32_e32 v11, 31, v10
	v_lshlrev_b64 v[10:11], 15, v[10:11]
	v_lshl_add_u64 v[10:11], s[50:51], 0, v[10:11]
	v_lshl_add_u64 v[8:9], v[10:11], 0, v[8:9]
	s_waitcnt vmcnt(15)
	v_lshlrev_b32_e32 v0, 16, v140
	v_and_b32_e32 v2, 0xffff0000, v140
	v_mul_f32_e32 v0, v36, v0
	v_mul_f32_e32 v2, v37, v2
	v_cvt_pk_bf16_f32 v2, v0, v2
	v_lshlrev_b32_e32 v0, 16, v141
	v_and_b32_e32 v3, 0xffff0000, v141
	v_mul_f32_e32 v3, v39, v3
	v_mul_f32_e32 v0, v38, v0
	v_cvt_pk_bf16_f32 v3, v0, v3
	global_store_dwordx2 v[8:9], v[2:3], off offset:16
	v_or_b32_e32 v2, v14, v221
	v_ashrrev_i32_e32 v3, 31, v2
	v_lshlrev_b64 v[2:3], 10, v[2:3]
	v_lshl_add_u64 v[2:3], v[172:173], 0, v[2:3]
	v_or_b32_e32 v8, s2, v222
	v_ashrrev_i32_e32 v9, 31, v8
	v_lshlrev_b64 v[8:9], 15, v[8:9]
	v_lshl_add_u64 v[8:9], s[50:51], 0, v[8:9]
	v_lshl_add_u64 v[6:7], v[8:9], 0, v[6:7]
	s_waitcnt vmcnt(15)
	v_lshlrev_b32_e32 v0, 16, v142
	v_and_b32_e32 v2, 0xffff0000, v142
	v_mul_f32_e32 v0, v40, v0
	v_mul_f32_e32 v2, v41, v2
	v_cvt_pk_bf16_f32 v2, v0, v2
	v_lshlrev_b32_e32 v0, 16, v143
	v_and_b32_e32 v3, 0xffff0000, v143
	v_mul_f32_e32 v3, v43, v3
	v_mul_f32_e32 v0, v42, v0
	v_cvt_pk_bf16_f32 v3, v0, v3
	global_store_dwordx2 v[6:7], v[2:3], off offset:1024
	v_or_b32_e32 v2, v14, v223
	v_ashrrev_i32_e32 v3, 31, v2
	v_lshlrev_b64 v[2:3], 10, v[2:3]
	v_lshl_add_u64 v[2:3], v[172:173], 0, v[2:3]
	v_or_b32_e32 v6, s2, v224
	v_ashrrev_i32_e32 v7, 31, v6
	v_lshlrev_b64 v[6:7], 15, v[6:7]
	v_lshl_add_u64 v[6:7], s[50:51], 0, v[6:7]
	v_lshl_add_u64 v[4:5], v[6:7], 0, v[4:5]
	s_waitcnt vmcnt(15)
	v_lshlrev_b32_e32 v0, 16, v144
	v_and_b32_e32 v2, 0xffff0000, v144
	v_mul_f32_e32 v0, v44, v0
	v_mul_f32_e32 v2, v45, v2
	v_cvt_pk_bf16_f32 v2, v0, v2
	v_lshlrev_b32_e32 v0, 16, v145
	v_and_b32_e32 v3, 0xffff0000, v145
	v_mul_f32_e32 v3, v47, v3
	v_mul_f32_e32 v0, v46, v0
	v_cvt_pk_bf16_f32 v3, v0, v3
	global_store_dwordx2 v[4:5], v[2:3], off offset:1024
	s_cbranch_scc1 .LBB0_223

.LBB0_254:
	ds_read_b128 v[2:5], v112
	ds_read_b128 v[6:9], v112 offset:32
	ds_read_b128 v[10:13], v112 offset:64
	v_readlane_b32 s52, v250, 43
	v_readlane_b32 s53, v250, 44
	s_andn2_b64 vcc, exec, s[52:53]
	s_waitcnt lgkmcnt(2)
	v_mfma_f32_32x32x16_bf16 v[96:111], v[2:5], v[114:117], 0
	ds_read_b128 v[2:5], v112 offset:96
	s_waitcnt lgkmcnt(2)
	v_mfma_f32_32x32x16_bf16 v[96:111], v[6:9], v[118:121], v[96:111]
	ds_read_b128 v[6:9], v112 offset:128
	s_waitcnt lgkmcnt(2)
	v_mfma_f32_32x32x16_bf16 v[96:111], v[10:13], v[122:125], v[96:111]
	ds_read_b128 v[10:13], v112 offset:160
	s_waitcnt lgkmcnt(2)
	v_mfma_f32_32x32x16_bf16 v[96:111], v[2:5], v[126:129], v[96:111]
	ds_read_b128 v[2:5], v112 offset:192
	s_waitcnt lgkmcnt(2)
	v_mfma_f32_32x32x16_bf16 v[96:111], v[6:9], v[130:133], v[96:111]
	ds_read_b128 v[6:9], v112 offset:224
	s_waitcnt lgkmcnt(2)
	v_mfma_f32_32x32x16_bf16 v[96:111], v[10:13], v[134:137], v[96:111]
	s_waitcnt lgkmcnt(1)
	v_mfma_f32_32x32x16_bf16 v[96:111], v[2:5], v[138:141], v[96:111]
	s_waitcnt lgkmcnt(0)
	v_mfma_f32_32x32x16_bf16 v[96:111], v[6:9], v[142:145], v[96:111]
	s_nop 11
	v_exp_f32_e32 v0, v96
	v_exp_f32_e32 v2, v97
	v_exp_f32_e32 v3, v98
	v_exp_f32_e32 v4, v99
	v_exp_f32_e32 v5, v100
	v_exp_f32_e32 v6, v101
	v_exp_f32_e32 v7, v102
	v_exp_f32_e32 v8, v103
	v_exp_f32_e32 v9, v104
	v_exp_f32_e32 v10, v105
	v_exp_f32_e32 v11, v106
	v_exp_f32_e32 v12, v107
	v_exp_f32_e32 v13, v108
	v_exp_f32_e32 v14, v109
	v_exp_f32_e32 v15, v110
	v_exp_f32_e32 v112, v111
	v_add_f32_e32 v0, 1.0, v0
	v_add_f32_e32 v2, 1.0, v2
	v_add_f32_e32 v3, 1.0, v3
	v_add_f32_e32 v113, 1.0, v4
	v_add_f32_e32 v176, 1.0, v5
	v_add_f32_e32 v177, 1.0, v6
	v_add_f32_e32 v228, 1.0, v7
	v_add_f32_e32 v8, 1.0, v8
	v_add_f32_e32 v9, 1.0, v9
	v_add_f32_e32 v229, 1.0, v10
	v_add_f32_e32 v230, 1.0, v11
	v_add_f32_e32 v231, 1.0, v12
	v_add_f32_e32 v232, 1.0, v13
	v_add_f32_e32 v233, 1.0, v14
	v_add_f32_e32 v234, 1.0, v15
	v_add_f32_e32 v235, 1.0, v112
	v_log_f32_e32 v4, v0
	v_log_f32_e32 v6, v2
	v_log_f32_e32 v7, v3
	v_log_f32_e32 v5, v113
	v_log_f32_e32 v10, v176
	v_log_f32_e32 v12, v177
	v_log_f32_e32 v13, v228
	v_log_f32_e32 v11, v8
	v_log_f32_e32 v8, v9
	v_log_f32_e32 v112, v229
	v_log_f32_e32 v15, v230
	v_log_f32_e32 v9, v231
	v_log_f32_e32 v14, v232
	v_log_f32_e32 v3, v233
	v_log_f32_e32 v2, v234
	v_log_f32_e32 v0, v235
	v_cndmask_b32_e64 v113, 0, 1, s[52:53]
	v_cmp_ne_u32_e64 s[0:1], 1, v113
	s_cbranch_vccnz .LBB0_256
	v_cndmask_b32_e64 v4, 0, -v4, s[6:7]
	v_cndmask_b32_e64 v6, 0, -v6, s[8:9]
	v_cndmask_b32_e64 v7, 0, -v7, s[10:11]
	v_cndmask_b32_e64 v5, 0, -v5, s[12:13]
	v_cndmask_b32_e64 v10, 0, -v10, s[14:15]
	v_cndmask_b32_e64 v12, 0, -v12, s[16:17]
	v_cndmask_b32_e64 v13, 0, -v13, s[18:19]
	v_cndmask_b32_e64 v11, 0, -v11, s[20:21]
	v_cndmask_b32_e64 v8, 0, -v8, s[22:23]
	v_cndmask_b32_e64 v176, 0, -v112, s[24:25]
	v_cndmask_b32_e64 v177, 0, -v15, s[26:27]
	v_cndmask_b32_e64 v9, 0, -v9, s[28:29]
	v_cndmask_b32_e64 v14, 0, -v14, s[30:31]
	v_cndmask_b32_e64 v112, 0, -v3, s[34:35]
	v_cndmask_b32_e64 v113, 0, -v2, s[36:37]
	v_cndmask_b32_e64 v15, 0, -v0, s[38:39]
	s_branch .LBB0_257

.LBB0_259:
	v_cvt_pk_bf16_f32 v98, v0, v5
	v_add_u32_e32 v0, v175, v191
	v_cvt_pk_bf16_f32 v99, v2, v3
	v_cvt_pk_bf16_f32 v100, v4, v13
	v_cvt_pk_bf16_f32 v101, v6, v7
	v_cvt_pk_bf16_f32 v2, v8, v9
	v_cvt_pk_bf16_f32 v3, v10, v11
	v_cvt_pk_bf16_f32 v4, v12, v97
	v_cvt_pk_bf16_f32 v5, v14, v15
	ds_read_b64_tr_b16 v[6:7], v0 offset:34816
	ds_read_b64_tr_b16 v[8:9], v0 offset:37376
	ds_read_b64_tr_b16 v[10:11], v0 offset:39936
	ds_read_b64_tr_b16 v[12:13], v0 offset:42496
	ds_read_b64_tr_b16 v[104:105], v0 offset:34880
	ds_read_b64_tr_b16 v[106:107], v0 offset:37440
	ds_read_b64_tr_b16 v[108:109], v0 offset:40000
	ds_read_b64_tr_b16 v[110:111], v0 offset:42560
	s_waitcnt lgkmcnt(6)
	v_mfma_f32_32x32x16_bf16 v[80:95], v[6:9], v[98:101], v[80:95]
	v_add_f32_e32 v96, v228, v229
	v_add_f32_e32 v96, v96, v230
	v_add_f32_e32 v227, v227, v96
	s_waitcnt lgkmcnt(4)
	v_mfma_f32_32x32x16_bf16 v[80:95], v[10:13], v[2:5], v[80:95]
	ds_read_b64_tr_b16 v[6:7], v0 offset:34944
	ds_read_b64_tr_b16 v[8:9], v0 offset:37504
	ds_read_b64_tr_b16 v[10:11], v0 offset:40064
	ds_read_b64_tr_b16 v[12:13], v0 offset:42624
	s_waitcnt lgkmcnt(6)
	v_mfma_f32_32x32x16_bf16 v[64:79], v[104:107], v[98:101], v[64:79]
	s_waitcnt lgkmcnt(4)
	v_mfma_f32_32x32x16_bf16 v[64:79], v[108:111], v[2:5], v[64:79]
	ds_read_b64_tr_b16 v[104:105], v0 offset:35008
	ds_read_b64_tr_b16 v[106:107], v0 offset:37568
	ds_read_b64_tr_b16 v[108:109], v0 offset:40128
	ds_read_b64_tr_b16 v[110:111], v0 offset:42688
	s_waitcnt lgkmcnt(6)
	v_mfma_f32_32x32x16_bf16 v[48:63], v[6:9], v[98:101], v[48:63]
	s_waitcnt lgkmcnt(4)
	v_mfma_f32_32x32x16_bf16 v[48:63], v[10:13], v[2:5], v[48:63]
	s_waitcnt lgkmcnt(2)
	v_mfma_f32_32x32x16_bf16 v[32:47], v[104:107], v[98:101], v[32:47]
	s_waitcnt lgkmcnt(0)
	v_mfma_f32_32x32x16_bf16 v[32:47], v[108:111], v[2:5], v[32:47]

.LBB0_563:
	s_and_b32 s13, s6, 0xff
	s_lshl_b32 s0, s13, 2
	v_mov_b32_e32 v0, s0
	global_load_dword v2, v0, s[38:39]
	s_lshl_b32 s4, s13, 6
	v_or_b32_e32 v0, s4, v174
	v_lshlrev_b32_e32 v3, 2, v0
	global_load_dword v21, v3, s[58:59]
	global_load_dword v20, v3, s[36:37]
	s_and_b32 s2, s10, 0x1800
	v_or_b32_e32 v1, s2, v182
	v_lshlrev_b32_e32 v1, 3, v1
	s_bfe_u32 s0, s12, 0x70001
	v_and_b32_e32 v1, 0xc180, v1
	v_or_b32_e32 v1, s0, v1
	v_lshlrev_b32_e32 v132, 10, v1
	v_lshl_add_u64 v[150:151], v[144:145], 0, v[132:133]
	v_lshl_add_u64 v[152:153], v[146:147], 0, v[132:133]
	v_lshl_add_u64 v[154:155], v[148:149], 0, v[132:133]
	v_lshlrev_b32_e32 v132, 6, v0
	v_lshl_add_u64 v[0:1], v[136:137], 0, v[132:133]
	global_load_dwordx4 v[4:7], v[0:1], off
	global_load_dwordx4 v[8:11], v[0:1], off offset:16
	v_lshl_add_u64 v[0:1], v[134:135], 0, v[132:133]
	global_load_dwordx4 v[12:15], v[0:1], off
	global_load_dwordx4 v[16:19], v[0:1], off offset:16
	v_or_b32_e32 v0, s4, v173
	v_lshlrev_b32_e32 v22, 2, v0
	v_or_b32_e32 v132, 0x800, v132
	s_bfe_u32 s16, s6, 0x70001
	v_mov_b32_e32 v188, 0
	v_mov_b32_e32 v189, v133
	s_waitcnt vmcnt(6)
	v_mul_f32_e32 v0, 0x3fb8aa3b, v2
	v_exp_f32_e32 v0, v0
	global_load_dword v2, v22, s[58:59]
	global_load_dword v1, v22, s[36:37]
	s_waitcnt vmcnt(7)
	v_mov_b32_e32 v22, v21
	v_mov_b32_e32 v25, v21
	v_mul_f32_e32 v23, v0, v21
	s_waitcnt vmcnt(6)
	v_mul_f32_e32 v24, v0, v20
	v_mul_f32_e32 v23, 0x3fb8aa3b, v23
	v_mul_f32_e32 v24, 0.15915494, v24
	v_exp_f32_e32 v23, v23
	v_sin_f32_e32 v26, v24
	v_cos_f32_e32 v24, v24
	v_mov_b32_e32 v27, v20
	v_mul_f32_e32 v28, v23, v26
	v_fma_f32 v29, v23, v24, -1.0
	v_mov_b32_e32 v24, v28
	v_mov_b32_e32 v26, v29
	v_pk_mul_f32 v[30:31], v[20:21], v[28:29]
	v_pk_mul_f32 v[22:23], v[22:23], v[24:25] op_sel_hi:[0,1]
	v_pk_mul_f32 v[20:21], v[20:21], v[26:27] op_sel_hi:[0,1]
	v_add_f32_e32 v28, v30, v31
	v_add_f32_e32 v21, v23, v21
	v_sub_f32_e32 v22, v22, v20
	v_div_scale_f32 v20, s[0:1], v21, v21, v28
	v_div_scale_f32 v24, s[0:1], v21, v21, v22
	v_rcp_f32_e32 v25, v20
	v_rcp_f32_e32 v26, v24
	v_div_scale_f32 v23, vcc, v28, v21, v28
	v_fma_f32 v29, -v20, v25, 1.0
	v_fma_f32 v30, -v24, v26, 1.0
	v_fmac_f32_e32 v25, v29, v25
	v_div_scale_f32 v27, s[0:1], v22, v21, v22
	v_fmac_f32_e32 v26, v30, v26
	v_mul_f32_e32 v29, v23, v25
	v_mul_f32_e32 v30, v27, v26
	v_fma_f32 v31, -v20, v29, v23
	v_fma_f32 v32, -v24, v30, v27
	v_fmac_f32_e32 v29, v31, v25
	v_fmac_f32_e32 v30, v32, v26
	v_fma_f32 v20, -v20, v29, v23
	v_fma_f32 v23, -v24, v30, v27
	v_div_fmas_f32 v20, v20, v25, v29
	s_mov_b64 vcc, s[0:1]
	v_div_fmas_f32 v23, v23, v26, v30
	v_div_fixup_f32 v22, v23, v21, v22
	v_div_fixup_f32 v20, v20, v21, v28
	s_waitcnt vmcnt(5)
	v_pk_mul_f32 v[24:25], v[4:5], v[22:23] op_sel_hi:[1,0]
	v_pk_mul_f32 v[26:27], v[6:7], v[22:23] op_sel_hi:[1,0]
	s_waitcnt vmcnt(4)
	v_pk_mul_f32 v[28:29], v[8:9], v[22:23] op_sel_hi:[1,0]
	v_pk_mul_f32 v[30:31], v[10:11], v[22:23] op_sel_hi:[1,0]
	s_waitcnt vmcnt(3)
	v_pk_mul_f32 v[32:33], v[12:13], v[22:23] op_sel_hi:[1,0]
	v_pk_mul_f32 v[34:35], v[14:15], v[22:23] op_sel_hi:[1,0]
	s_waitcnt vmcnt(2)
	v_pk_mul_f32 v[36:37], v[16:17], v[22:23] op_sel_hi:[1,0]
	v_pk_mul_f32 v[22:23], v[18:19], v[22:23] op_sel_hi:[1,0]
	v_pk_fma_f32 v[14:15], v[14:15], v[20:21], v[26:27] op_sel_hi:[1,0,1] neg_lo:[0,0,1] neg_hi:[0,0,1]
	v_pk_fma_f32 v[12:13], v[12:13], v[20:21], v[24:25] op_sel_hi:[1,0,1] neg_lo:[0,0,1] neg_hi:[0,0,1]
	v_pk_fma_f32 v[18:19], v[18:19], v[20:21], v[30:31] op_sel_hi:[1,0,1] neg_lo:[0,0,1] neg_hi:[0,0,1]
	v_pk_fma_f32 v[16:17], v[16:17], v[20:21], v[28:29] op_sel_hi:[1,0,1] neg_lo:[0,0,1] neg_hi:[0,0,1]
	v_pk_fma_f32 v[6:7], v[6:7], v[20:21], v[34:35] op_sel_hi:[1,0,1]
	v_pk_fma_f32 v[4:5], v[4:5], v[20:21], v[32:33] op_sel_hi:[1,0,1]
	v_pk_fma_f32 v[10:11], v[10:11], v[20:21], v[22:23] op_sel_hi:[1,0,1]
	v_pk_fma_f32 v[8:9], v[8:9], v[20:21], v[36:37] op_sel_hi:[1,0,1]
	v_cvt_pk_bf16_f32 v104, v12, v13
	v_cvt_pk_bf16_f32 v105, v14, v15
	v_cvt_pk_bf16_f32 v106, v16, v17
	v_cvt_pk_bf16_f32 v107, v18, v19
	v_cvt_pk_bf16_f32 v92, v4, v5
	v_cvt_pk_bf16_f32 v93, v6, v7
	s_nop 0
	v_cvt_pk_bf16_f32 v94, v8, v9
	v_cvt_pk_bf16_f32 v95, v10, v11
	v_lshl_or_b32 v58, s13, 12, v183
	v_mov_b32_e32 v59, 0
	v_lshl_add_u64 v[60:61], v[138:139], 0, v[58:59]
	v_lshl_add_u64 v[62:63], v[140:141], 0, v[58:59]
	global_load_dwordx4 v[196:199], v[60:61], off
	global_load_dwordx4 v[200:203], v[62:63], off
	global_load_dwordx4 v[204:207], v[60:61], off offset:32
	global_load_dwordx4 v[208:211], v[62:63], off offset:32
	global_load_dwordx4 v[212:215], v[60:61], off offset:64
	global_load_dwordx4 v[216:219], v[62:63], off offset:64
	global_load_dwordx4 v[220:223], v[60:61], off offset:96
	global_load_dwordx4 v[224:227], v[62:63], off offset:96
	global_load_dwordx4 v[228:231], v[60:61], off offset:128
	global_load_dwordx4 v[232:235], v[62:63], off offset:128
	global_load_dwordx4 v[236:239], v[60:61], off offset:160
	global_load_dwordx4 v[240:243], v[62:63], off offset:160
	global_load_dwordx4 v[244:247], v[60:61], off offset:192
	global_load_dwordx4 v[40:43], v[62:63], off offset:192
	global_load_dwordx4 v[44:47], v[60:61], off offset:224
	global_load_dwordx4 v[48:51], v[62:63], off offset:224
	global_load_dword v21, v3, s[58:59] offset:128
	global_load_dword v20, v3, s[36:37] offset:128
	v_lshl_add_u64 v[12:13], v[136:137], 0, v[132:133]
	v_lshl_add_u64 v[22:23], v[134:135], 0, v[132:133]
	global_load_dwordx4 v[4:7], v[12:13], off
	global_load_dwordx4 v[8:11], v[12:13], off offset:16
	s_nop 0
	global_load_dwordx4 v[12:15], v[22:23], off
	global_load_dwordx4 v[16:19], v[22:23], off offset:16
	v_lshl_or_b32 v132, s13, 12, v183
	v_lshl_add_u64 v[22:23], v[138:139], 0, v[132:133]
	s_waitcnt vmcnt(7)
	v_mul_f32_e32 v2, v2, v0
	v_mul_f32_e32 v2, 0x3fb8aa3b, v2
	v_exp_f32_e32 v2, v2
	s_waitcnt vmcnt(5)
	v_mul_f32_e32 v3, v0, v21
	s_waitcnt vmcnt(4)
	v_mul_f32_e32 v25, v0, v20
	v_mul_f32_e32 v3, 0x3fb8aa3b, v3
	v_mul_f32_e32 v25, 0.15915494, v25
	v_exp_f32_e32 v3, v3
	v_sin_f32_e32 v26, v25
	v_cos_f32_e32 v25, v25
	v_mov_b32_e32 v24, v21
	v_mov_b32_e32 v27, v21
	v_mul_f32_e32 v30, v3, v26
	v_fma_f32 v31, v3, v25, -1.0
	v_mov_b32_e32 v29, v20
	v_mov_b32_e32 v26, v30
	v_mov_b32_e32 v28, v31
	v_pk_mul_f32 v[32:33], v[20:21], v[30:31]
	v_pk_mul_f32 v[24:25], v[24:25], v[26:27] op_sel_hi:[0,1]
	v_pk_mul_f32 v[20:21], v[20:21], v[28:29] op_sel_hi:[0,1]
	v_add_f32_e32 v3, v32, v33
	v_add_f32_e32 v21, v25, v21
	v_sub_f32_e32 v24, v24, v20
	v_div_scale_f32 v20, s[0:1], v21, v21, v3
	v_div_scale_f32 v26, s[0:1], v21, v21, v24
	v_rcp_f32_e32 v27, v20
	v_rcp_f32_e32 v28, v26
	v_div_scale_f32 v25, vcc, v3, v21, v3
	v_fma_f32 v30, -v20, v27, 1.0
	v_fma_f32 v31, -v26, v28, 1.0
	v_fmac_f32_e32 v27, v30, v27
	v_div_scale_f32 v29, s[0:1], v24, v21, v24
	v_fmac_f32_e32 v28, v31, v28
	v_mul_f32_e32 v30, v25, v27
	v_mul_f32_e32 v31, v29, v28
	v_fma_f32 v32, -v20, v30, v25
	v_fma_f32 v33, -v26, v31, v29
	v_fmac_f32_e32 v30, v32, v27
	v_fmac_f32_e32 v31, v33, v28
	v_fma_f32 v20, -v20, v30, v25
	v_fma_f32 v25, -v26, v31, v29
	v_div_fmas_f32 v20, v20, v27, v30
	s_mov_b64 vcc, s[0:1]
	v_div_fixup_f32 v20, v20, v21, v3
	v_div_fmas_f32 v3, v25, v28, v31
	v_div_fixup_f32 v24, v3, v21, v24
	s_waitcnt vmcnt(3)
	v_pk_mul_f32 v[26:27], v[4:5], v[24:25] op_sel_hi:[1,0]
	v_pk_mul_f32 v[28:29], v[6:7], v[24:25] op_sel_hi:[1,0]
	s_waitcnt vmcnt(2)
	v_pk_mul_f32 v[30:31], v[8:9], v[24:25] op_sel_hi:[1,0]
	v_pk_mul_f32 v[32:33], v[10:11], v[24:25] op_sel_hi:[1,0]
	s_waitcnt vmcnt(1)
	v_pk_mul_f32 v[34:35], v[12:13], v[24:25] op_sel_hi:[1,0]
	v_pk_mul_f32 v[36:37], v[14:15], v[24:25] op_sel_hi:[1,0]
	s_waitcnt vmcnt(0)
	v_pk_mul_f32 v[38:39], v[16:17], v[24:25] op_sel_hi:[1,0]
	v_pk_mul_f32 v[24:25], v[18:19], v[24:25] op_sel_hi:[1,0]
	v_pk_fma_f32 v[12:13], v[12:13], v[20:21], v[26:27] op_sel_hi:[1,0,1] neg_lo:[0,0,1] neg_hi:[0,0,1]
	v_pk_fma_f32 v[6:7], v[6:7], v[20:21], v[36:37] op_sel_hi:[1,0,1]
	v_pk_fma_f32 v[4:5], v[4:5], v[20:21], v[34:35] op_sel_hi:[1,0,1]
	v_pk_fma_f32 v[10:11], v[10:11], v[20:21], v[24:25] op_sel_hi:[1,0,1]
	v_pk_fma_f32 v[8:9], v[8:9], v[20:21], v[38:39] op_sel_hi:[1,0,1]
	v_cvt_pk_bf16_f32 v116, v12, v13
	v_lshl_add_u64 v[12:13], v[140:141], 0, v[132:133]
	v_pk_fma_f32 v[14:15], v[14:15], v[20:21], v[28:29] op_sel_hi:[1,0,1] neg_lo:[0,0,1] neg_hi:[0,0,1]
	v_pk_fma_f32 v[18:19], v[18:19], v[20:21], v[32:33] op_sel_hi:[1,0,1] neg_lo:[0,0,1] neg_hi:[0,0,1]
	v_pk_fma_f32 v[16:17], v[16:17], v[20:21], v[30:31] op_sel_hi:[1,0,1] neg_lo:[0,0,1] neg_hi:[0,0,1]
	v_cvt_pk_bf16_f32 v117, v14, v15
	s_lshl_b32 s1, s6, 3
	v_cvt_pk_bf16_f32 v118, v16, v17
	v_cvt_pk_bf16_f32 v119, v18, v19
	v_cvt_pk_bf16_f32 v112, v4, v5
	v_cvt_pk_bf16_f32 v113, v6, v7
	v_cvt_pk_bf16_f32 v114, v8, v9
	v_cvt_pk_bf16_f32 v115, v10, v11
	s_and_b32 s15, s1, 0x1800
	v_or_b32_e32 v3, s15, v174
	v_lshlrev_b32_e32 v3, 3, v3
	s_lshl_b32 s0, s6, 4
	v_and_b32_e32 v3, 0xc080, v3
	s_and_b32 s14, s0, 16
	v_or_b32_e32 v3, s16, v3
	v_or_b32_e32 v132, s14, v176
	v_lshl_or_b32 v3, v3, 9, v177
	v_or3_b32 v14, s14, v175, v3
	v_or_b32_e32 v3, v3, v132
	v_lshlrev_b32_e32 v3, 1, v3
	v_lshlrev_b32_e32 v14, 1, v14
	v_or_b32_e32 v15, 16, v3
	v_mul_f32_e32 v0, v0, v1
	v_mul_f32_e32 v1, 0.15915494, v0
	v_cos_f32_e32 v0, v1
	v_sin_f32_e32 v1, v1
	s_mov_b64 s[0:1], 0
	s_mov_b32 s16, 0
	v_pk_mul_f32 v[198:199], v[126:127], v[198:199]
	v_pk_mul_f32 v[196:197], v[124:125], v[196:197]
	v_pk_mul_f32 v[202:203], v[130:131], v[202:203]
	v_pk_mul_f32 v[200:201], v[128:129], v[200:201]
	s_nop 0
	v_cvt_pk_bf16_f32 v64, v196, v200
	v_cvt_pk_bf16_f32 v65, v197, v201
	v_cvt_pk_bf16_f32 v66, v198, v202
	v_cvt_pk_bf16_f32 v67, v199, v203
	v_pk_mul_f32 v[206:207], v[126:127], v[206:207]
	v_pk_mul_f32 v[204:205], v[124:125], v[204:205]
	v_pk_mul_f32 v[210:211], v[130:131], v[210:211]
	v_pk_mul_f32 v[208:209], v[128:129], v[208:209]
	s_nop 0
	v_cvt_pk_bf16_f32 v68, v204, v208
	v_cvt_pk_bf16_f32 v69, v205, v209
	v_cvt_pk_bf16_f32 v70, v206, v210
	v_cvt_pk_bf16_f32 v71, v207, v211
	v_pk_mul_f32 v[214:215], v[126:127], v[214:215]
	v_pk_mul_f32 v[212:213], v[124:125], v[212:213]
	v_pk_mul_f32 v[218:219], v[130:131], v[218:219]
	v_pk_mul_f32 v[216:217], v[128:129], v[216:217]
	s_nop 0
	v_cvt_pk_bf16_f32 v72, v212, v216
	v_cvt_pk_bf16_f32 v73, v213, v217
	v_cvt_pk_bf16_f32 v74, v214, v218
	v_cvt_pk_bf16_f32 v75, v215, v219
	v_pk_mul_f32 v[222:223], v[126:127], v[222:223]
	v_pk_mul_f32 v[220:221], v[124:125], v[220:221]
	v_pk_mul_f32 v[226:227], v[130:131], v[226:227]
	v_pk_mul_f32 v[224:225], v[128:129], v[224:225]
	s_nop 0
	v_cvt_pk_bf16_f32 v76, v220, v224
	v_cvt_pk_bf16_f32 v77, v221, v225
	v_cvt_pk_bf16_f32 v78, v222, v226
	v_cvt_pk_bf16_f32 v79, v223, v227
	v_pk_mul_f32 v[230:231], v[126:127], v[230:231]
	v_pk_mul_f32 v[228:229], v[124:125], v[228:229]
	v_pk_mul_f32 v[234:235], v[130:131], v[234:235]
	v_pk_mul_f32 v[232:233], v[128:129], v[232:233]
	s_nop 0
	v_cvt_pk_bf16_f32 v84, v228, v232
	v_cvt_pk_bf16_f32 v85, v229, v233
	v_cvt_pk_bf16_f32 v86, v230, v234
	v_cvt_pk_bf16_f32 v87, v231, v235
	v_pk_mul_f32 v[238:239], v[126:127], v[238:239]
	v_pk_mul_f32 v[236:237], v[124:125], v[236:237]
	v_pk_mul_f32 v[242:243], v[130:131], v[242:243]
	v_pk_mul_f32 v[240:241], v[128:129], v[240:241]
	s_nop 0
	v_cvt_pk_bf16_f32 v88, v236, v240
	v_cvt_pk_bf16_f32 v89, v237, v241
	v_cvt_pk_bf16_f32 v90, v238, v242
	v_cvt_pk_bf16_f32 v91, v239, v243
	v_pk_mul_f32 v[246:247], v[126:127], v[246:247]
	v_pk_mul_f32 v[244:245], v[124:125], v[244:245]
	v_pk_mul_f32 v[42:43], v[130:131], v[42:43]
	v_pk_mul_f32 v[40:41], v[128:129], v[40:41]
	s_nop 0
	v_cvt_pk_bf16_f32 v96, v244, v40
	v_cvt_pk_bf16_f32 v97, v245, v41
	v_cvt_pk_bf16_f32 v98, v246, v42
	v_cvt_pk_bf16_f32 v99, v247, v43
	v_lshl_add_u64 v[12:13], v[142:143], 0, s[4:5]
	s_bfe_u32 s4, s6, 0x10001
	v_pk_mul_f32 v[46:47], v[126:127], v[46:47]
	v_pk_mul_f32 v[44:45], v[124:125], v[44:45]
	v_pk_mul_f32 v[50:51], v[130:131], v[50:51]
	v_pk_mul_f32 v[48:49], v[128:129], v[48:49]
	s_nop 0
	v_cvt_pk_bf16_f32 v108, v44, v48
	v_cvt_pk_bf16_f32 v109, v45, v49
	v_cvt_pk_bf16_f32 v110, v46, v50
	v_cvt_pk_bf16_f32 v111, v47, v51
	global_load_dwordx4 v[100:103], v[12:13], off
	global_load_dwordx4 v[80:83], v[12:13], off offset:32
	global_load_dwordx4 v[120:123], v14, s[54:55]
	global_load_dwordx2 v[158:159], v3, s[54:55]
	global_load_dwordx2 v[156:157], v15, s[54:55]
	v_or_b32_e32 v3, s2, v174
	v_pk_mul_f32 v[160:161], v[0:1], v[2:3] op_sel_hi:[1,0]
	v_lshrrev_b32_e32 v187, 3, v3
	v_pk_mov_b32 v[162:163], v[160:161], v[160:161] op_sel:[1,0]
	v_mov_b32_e32 v164, v160
	v_mov_b32_e32 v165, v160
	v_mov_b32_e32 v166, v161
	v_mov_b32_e32 v167, v161
	v_mov_b32_e32 v246, 0xbdd2d3e8
	global_load_dwordx4 v[238:241], v[152:153], off
	global_load_dwordx2 v[242:243], v[154:155], off
	global_load_dwordx2 v[244:245], v[150:151], off
.Lscan_tile:
	s_waitcnt vmcnt(3)
	v_mfma_f32_32x32x16_bf16 v[0:15], v[120:123], v[104:107], 0
	v_mfma_f32_32x32x16_bf16 v[16:31], v[120:123], v[116:119], 0
	v_mfma_f32_32x32x16_bf16 v[32:47], v[120:123], v[92:95], 0
	v_mfma_f32_32x32x16_bf16 v[196:211], v[120:123], v[112:115], 0
	s_and_b32 s18, s16, 0x2000
	s_and_b32 s17, s2, 0x1f00
	s_or_b32 s17, s17, s13
	s_lshl_b32 s17, s17, 12
	s_and_b32 s17, s17, 0x1ffc000
	s_addk_i32 s16, 0x800
	v_add_u32_e32 v222, s2, v174
	v_and_or_b32 v223, v187, 14, s4
	v_lshlrev_b32_e32 v225, 5, v222
	v_lshlrev_b32_e32 v226, 1, v222
	v_lshl_or_b32 v227, v223, 9, s18
	v_and_b32_e32 v222, 0x1e0, v225
	v_and_b32_e32 v223, 16, v226
	v_or_b32_e32 v224, v222, v132
	v_bitop3_b32 v222, v222, v223, v132 bitop3:0x36
	v_or_b32_e32 v225, s17, v227
	v_bitop3_b32 v226, v224, v223, 8 bitop3:0x36
	v_or_b32_e32 v227, v222, v225
	s_cmp_eq_u32 s0, 0
	s_cbranch_scc1 .Lscan_nogelu
	v_fmac_f32_e32 v48, v100, v228
	v_fmac_f32_e32 v49, v101, v229
	v_fmac_f32_e32 v50, v102, v230
	v_fmac_f32_e32 v51, v103, v231
	v_fmac_f32_e32 v52, v80, v232
	v_fmac_f32_e32 v53, v81, v233
	v_fmac_f32_e32 v54, v82, v234
	v_fmac_f32_e32 v55, v83, v235
	v_mul_f32_e32 v56, v48, v48
	v_mul_f32_e32 v57, v49, v49
	v_mul_f32_e32 v58, v50, v50
	v_mul_f32_e32 v59, v51, v51
	v_mul_f32_e32 v60, v52, v52
	v_mul_f32_e32 v61, v53, v53
	v_mul_f32_e32 v62, v54, v54
	v_mul_f32_e32 v63, v55, v55
	v_fmaak_f32 v56, v56, v246, 0xc0135761
	v_fmaak_f32 v57, v57, v246, 0xc0135761
	v_fmaak_f32 v58, v58, v246, 0xc0135761
	v_fmaak_f32 v59, v59, v246, 0xc0135761
	v_fmaak_f32 v60, v60, v246, 0xc0135761
	v_fmaak_f32 v61, v61, v246, 0xc0135761
	v_fmaak_f32 v62, v62, v246, 0xc0135761
	v_fmaak_f32 v63, v63, v246, 0xc0135761
	v_mul_f32_e32 v56, v48, v56
	v_mul_f32_e32 v57, v49, v57
	v_mul_f32_e32 v58, v50, v58
	v_mul_f32_e32 v59, v51, v59
	v_mul_f32_e32 v60, v52, v60
	v_mul_f32_e32 v61, v53, v61
	v_mul_f32_e32 v62, v54, v62
	v_mul_f32_e32 v63, v55, v63
	v_exp_f32_e32 v56, v56
	v_exp_f32_e32 v57, v57
	v_exp_f32_e32 v58, v58
	v_exp_f32_e32 v59, v59
	v_exp_f32_e32 v60, v60
	v_exp_f32_e32 v61, v61
	v_exp_f32_e32 v62, v62
	v_exp_f32_e32 v63, v63
	v_add_f32_e32 v56, 1.0, v56
	v_add_f32_e32 v57, 1.0, v57
	v_add_f32_e32 v58, 1.0, v58
	v_add_f32_e32 v59, 1.0, v59
	v_add_f32_e32 v60, 1.0, v60
	v_add_f32_e32 v61, 1.0, v61
	v_add_f32_e32 v62, 1.0, v62
	v_add_f32_e32 v63, 1.0, v63
	v_rcp_f32_e32 v56, v56
	v_rcp_f32_e32 v57, v57
	v_rcp_f32_e32 v58, v58
	v_rcp_f32_e32 v59, v59
	v_rcp_f32_e32 v60, v60
	v_rcp_f32_e32 v61, v61
	v_rcp_f32_e32 v62, v62
	v_rcp_f32_e32 v63, v63
	v_mul_f32_e32 v48, v48, v56
	v_mul_f32_e32 v49, v49, v57
	v_mul_f32_e32 v50, v50, v58
	v_mul_f32_e32 v51, v51, v59
	v_mul_f32_e32 v52, v52, v60
	v_mul_f32_e32 v53, v53, v61
	v_mul_f32_e32 v54, v54, v62
	v_mul_f32_e32 v55, v55, v63
	v_cvt_pk_bf16_f32 v56, v48, v49
	v_cvt_pk_bf16_f32 v57, v50, v51
	v_cvt_pk_bf16_f32 v58, v52, v53
	v_cvt_pk_bf16_f32 v59, v54, v55
	global_store_dwordx2 v236, v[56:57], s[90:91]
	global_store_dwordx2 v237, v[58:59], s[90:91]
.Lscan_nogelu:
	v_lshlrev_b32_e32 v228, 16, v158
	v_and_b32_e32 v229, 0xffff0000, v158
	v_lshlrev_b32_e32 v230, 16, v159
	v_and_b32_e32 v231, 0xffff0000, v159
	v_lshlrev_b32_e32 v232, 16, v156
	v_and_b32_e32 v233, 0xffff0000, v156
	v_lshlrev_b32_e32 v234, 16, v157
	v_and_b32_e32 v235, 0xffff0000, v157
	v_or_b32_e32 v237, v226, v225
	v_lshlrev_b32_e32 v236, 1, v227
	v_lshlrev_b32_e32 v237, 1, v237
	s_add_u32 s0, s0, 0x40000
	s_addc_u32 s1, s1, 0
	v_lshl_add_u64 v[216:217], v[152:153], 0, s[0:1]
	v_lshl_add_u64 v[218:219], v[154:155], 0, s[0:1]
	v_lshl_add_u64 v[220:221], v[150:151], 0, s[0:1]
	global_load_dwordx4 v[120:123], v[216:217], off
	global_load_dwordx2 v[158:159], v[218:219], off
	global_load_dwordx2 v[156:157], v[220:221], off
	v_permlane32_swap_b32_e32 v0, v16
	v_permlane32_swap_b32_e32 v1, v17
	v_permlane32_swap_b32_e32 v2, v18
	v_permlane32_swap_b32_e32 v3, v19
	v_permlane32_swap_b32_e32 v4, v20
	v_permlane32_swap_b32_e32 v5, v21
	v_permlane32_swap_b32_e32 v6, v22
	v_permlane32_swap_b32_e32 v7, v23
	v_permlane32_swap_b32_e32 v8, v24
	v_permlane32_swap_b32_e32 v9, v25
	v_permlane32_swap_b32_e32 v10, v26
	v_permlane32_swap_b32_e32 v11, v27
	v_permlane32_swap_b32_e32 v12, v28
	v_permlane32_swap_b32_e32 v13, v29
	v_permlane32_swap_b32_e32 v14, v30
	v_permlane32_swap_b32_e32 v15, v31
	v_permlane32_swap_b32_e32 v32, v196
	v_permlane32_swap_b32_e32 v33, v197
	v_permlane32_swap_b32_e32 v34, v198
	v_permlane32_swap_b32_e32 v35, v199
	v_permlane32_swap_b32_e32 v36, v200
	v_permlane32_swap_b32_e32 v37, v201
	v_permlane32_swap_b32_e32 v38, v202
	v_permlane32_swap_b32_e32 v39, v203
	v_permlane32_swap_b32_e32 v40, v204
	v_permlane32_swap_b32_e32 v41, v205
	v_permlane32_swap_b32_e32 v42, v206
	v_permlane32_swap_b32_e32 v43, v207
	v_permlane32_swap_b32_e32 v44, v208
	v_permlane32_swap_b32_e32 v45, v209
	v_permlane32_swap_b32_e32 v46, v210
	v_permlane32_swap_b32_e32 v47, v211
	v_fmac_f32_e32 v0, v160, v188
	v_fmac_f32_e32 v32, v160, v189
	v_fma_f32 v0, -v161, v189, v0
	v_fmac_f32_e32 v32, v161, v188
	v_fmac_f32_e32 v1, v160, v0
	v_fmac_f32_e32 v33, v160, v32
	v_cvt_pk_bf16_f32 v212, v0, v32
	v_fma_f32 v1, -v161, v32, v1
	v_fmac_f32_e32 v33, v161, v0
	ds_write_b32 v185, v212 offset:18432
	v_fmac_f32_e32 v2, v160, v1
	v_fmac_f32_e32 v34, v160, v33
	v_cvt_pk_bf16_f32 v213, v1, v33
	v_fma_f32 v2, -v161, v33, v2
	v_fmac_f32_e32 v34, v161, v1
	ds_write_b32 v185, v213 offset:18704
	v_fmac_f32_e32 v3, v160, v2
	v_fmac_f32_e32 v35, v160, v34
	v_cvt_pk_bf16_f32 v214, v2, v34
	v_fma_f32 v3, -v161, v34, v3
	v_fmac_f32_e32 v35, v161, v2
	ds_write_b32 v185, v214 offset:18976
	v_fmac_f32_e32 v16, v160, v3
	v_fmac_f32_e32 v196, v160, v35
	v_cvt_pk_bf16_f32 v215, v3, v35
	v_fma_f32 v16, -v161, v35, v16
	v_fmac_f32_e32 v196, v161, v3
	ds_write_b32 v185, v215 offset:19248
	v_fmac_f32_e32 v17, v160, v16
	v_fmac_f32_e32 v197, v160, v196
	v_cvt_pk_bf16_f32 v212, v16, v196
	v_fma_f32 v17, -v161, v196, v17
	v_fmac_f32_e32 v197, v161, v16
	ds_write_b32 v185, v212 offset:19520
	v_fmac_f32_e32 v18, v160, v17
	v_fmac_f32_e32 v198, v160, v197
	v_cvt_pk_bf16_f32 v213, v17, v197
	v_fma_f32 v18, -v161, v197, v18
	v_fmac_f32_e32 v198, v161, v17
	ds_write_b32 v185, v213 offset:19792
	v_fmac_f32_e32 v19, v160, v18
	v_fmac_f32_e32 v199, v160, v198
	v_cvt_pk_bf16_f32 v214, v18, v198
	v_fma_f32 v19, -v161, v198, v19
	v_fmac_f32_e32 v199, v161, v18
	ds_write_b32 v185, v214 offset:20064
	v_fmac_f32_e32 v4, v160, v19
	v_fmac_f32_e32 v36, v160, v199
	v_cvt_pk_bf16_f32 v215, v19, v199
	v_fma_f32 v4, -v161, v199, v4
	v_fmac_f32_e32 v36, v161, v19
	ds_write_b32 v185, v215 offset:20336
	v_fmac_f32_e32 v5, v160, v4
	v_fmac_f32_e32 v37, v160, v36
	v_cvt_pk_bf16_f32 v212, v4, v36
	v_fma_f32 v5, -v161, v36, v5
	v_fmac_f32_e32 v37, v161, v4
	ds_write_b32 v185, v212 offset:20608
	v_fmac_f32_e32 v6, v160, v5
	v_fmac_f32_e32 v38, v160, v37
	v_cvt_pk_bf16_f32 v213, v5, v37
	v_fma_f32 v6, -v161, v37, v6
	v_fmac_f32_e32 v38, v161, v5
	ds_write_b32 v185, v213 offset:20880
	v_fmac_f32_e32 v7, v160, v6
	v_fmac_f32_e32 v39, v160, v38
	v_cvt_pk_bf16_f32 v214, v6, v38
	v_fma_f32 v7, -v161, v38, v7
	v_fmac_f32_e32 v39, v161, v6
	ds_write_b32 v185, v214 offset:21152
	v_fmac_f32_e32 v20, v160, v7
	v_fmac_f32_e32 v200, v160, v39
	v_cvt_pk_bf16_f32 v215, v7, v39
	v_fma_f32 v20, -v161, v39, v20
	v_fmac_f32_e32 v200, v161, v7
	ds_write_b32 v185, v215 offset:21424
	v_fmac_f32_e32 v21, v160, v20
	v_fmac_f32_e32 v201, v160, v200
	v_cvt_pk_bf16_f32 v212, v20, v200
	v_fma_f32 v21, -v161, v200, v21
	v_fmac_f32_e32 v201, v161, v20
	ds_write_b32 v185, v212 offset:21696
	v_fmac_f32_e32 v22, v160, v21
	v_fmac_f32_e32 v202, v160, v201
	v_cvt_pk_bf16_f32 v213, v21, v201
	v_fma_f32 v22, -v161, v201, v22
	v_fmac_f32_e32 v202, v161, v21
	ds_write_b32 v185, v213 offset:21968
	v_fmac_f32_e32 v23, v160, v22
	v_fmac_f32_e32 v203, v160, v202
	v_cvt_pk_bf16_f32 v214, v22, v202
	v_fma_f32 v23, -v161, v202, v23
	v_fmac_f32_e32 v203, v161, v22
	ds_write_b32 v185, v214 offset:22240
	v_fmac_f32_e32 v8, v160, v23
	v_fmac_f32_e32 v40, v160, v203
	v_cvt_pk_bf16_f32 v215, v23, v203
	v_fma_f32 v8, -v161, v203, v8
	v_fmac_f32_e32 v40, v161, v23
	ds_write_b32 v185, v215 offset:22512
	v_fmac_f32_e32 v9, v160, v8
	v_fmac_f32_e32 v41, v160, v40
	v_cvt_pk_bf16_f32 v212, v8, v40
	v_fma_f32 v9, -v161, v40, v9
	v_fmac_f32_e32 v41, v161, v8
	ds_write_b32 v185, v212 offset:22784
	v_fmac_f32_e32 v10, v160, v9
	v_fmac_f32_e32 v42, v160, v41
	v_cvt_pk_bf16_f32 v213, v9, v41
	v_fma_f32 v10, -v161, v41, v10
	v_fmac_f32_e32 v42, v161, v9
	ds_write_b32 v185, v213 offset:23056
	v_fmac_f32_e32 v11, v160, v10
	v_fmac_f32_e32 v43, v160, v42
	v_cvt_pk_bf16_f32 v214, v10, v42
	v_fma_f32 v11, -v161, v42, v11
	v_fmac_f32_e32 v43, v161, v10
	ds_write_b32 v185, v214 offset:23328
	v_fmac_f32_e32 v24, v160, v11
	v_fmac_f32_e32 v204, v160, v43
	v_cvt_pk_bf16_f32 v215, v11, v43
	v_fma_f32 v24, -v161, v43, v24
	v_fmac_f32_e32 v204, v161, v11
	ds_write_b32 v185, v215 offset:23600
	v_fmac_f32_e32 v25, v160, v24
	v_fmac_f32_e32 v205, v160, v204
	v_cvt_pk_bf16_f32 v212, v24, v204
	v_fma_f32 v25, -v161, v204, v25
	v_fmac_f32_e32 v205, v161, v24
	ds_write_b32 v185, v212 offset:23872
	v_fmac_f32_e32 v26, v160, v25
	v_fmac_f32_e32 v206, v160, v205
	v_cvt_pk_bf16_f32 v213, v25, v205
	v_fma_f32 v26, -v161, v205, v26
	v_fmac_f32_e32 v206, v161, v25
	ds_write_b32 v185, v213 offset:24144
	v_fmac_f32_e32 v27, v160, v26
	v_fmac_f32_e32 v207, v160, v206
	v_cvt_pk_bf16_f32 v214, v26, v206
	v_fma_f32 v27, -v161, v206, v27
	v_fmac_f32_e32 v207, v161, v26
	ds_write_b32 v185, v214 offset:24416
	v_fmac_f32_e32 v12, v160, v27
	v_fmac_f32_e32 v44, v160, v207
	v_cvt_pk_bf16_f32 v215, v27, v207
	v_fma_f32 v12, -v161, v207, v12
	v_fmac_f32_e32 v44, v161, v27
	ds_write_b32 v185, v215 offset:24688
	v_fmac_f32_e32 v13, v160, v12
	v_fmac_f32_e32 v45, v160, v44
	v_cvt_pk_bf16_f32 v212, v12, v44
	v_fma_f32 v13, -v161, v44, v13
	v_fmac_f32_e32 v45, v161, v12
	ds_write_b32 v185, v212 offset:24960
	v_fmac_f32_e32 v14, v160, v13
	v_fmac_f32_e32 v46, v160, v45
	v_cvt_pk_bf16_f32 v213, v13, v45
	v_fma_f32 v14, -v161, v45, v14
	v_fmac_f32_e32 v46, v161, v13
	ds_write_b32 v185, v213 offset:25232
	v_fmac_f32_e32 v15, v160, v14
	v_fmac_f32_e32 v47, v160, v46
	v_cvt_pk_bf16_f32 v214, v14, v46
	v_fma_f32 v15, -v161, v46, v15
	v_fmac_f32_e32 v47, v161, v14
	ds_write_b32 v185, v214 offset:25504
	v_fmac_f32_e32 v28, v160, v15
	v_fmac_f32_e32 v208, v160, v47
	v_cvt_pk_bf16_f32 v215, v15, v47
	v_fma_f32 v28, -v161, v47, v28
	v_fmac_f32_e32 v208, v161, v15
	ds_write_b32 v185, v215 offset:25776
	v_fmac_f32_e32 v29, v160, v28
	v_fmac_f32_e32 v209, v160, v208
	v_cvt_pk_bf16_f32 v212, v28, v208
	v_fma_f32 v29, -v161, v208, v29
	v_fmac_f32_e32 v209, v161, v28
	ds_write_b32 v185, v212 offset:26048
	v_fmac_f32_e32 v30, v160, v29
	v_fmac_f32_e32 v210, v160, v209
	v_cvt_pk_bf16_f32 v213, v29, v209
	v_fma_f32 v30, -v161, v209, v30
	v_fmac_f32_e32 v210, v161, v29
	ds_write_b32 v185, v213 offset:26320
	v_fmac_f32_e32 v31, v160, v30
	v_fmac_f32_e32 v211, v160, v210
	v_cvt_pk_bf16_f32 v214, v30, v210
	v_fma_f32 v31, -v161, v210, v31
	v_fmac_f32_e32 v211, v161, v30
	ds_write_b32 v185, v214 offset:26592
	v_mov_b32_e32 v188, v31
	v_mov_b32_e32 v189, v211
	v_cvt_pk_bf16_f32 v215, v31, v211
	ds_write_b32 v185, v215 offset:26864
	s_waitcnt lgkmcnt(0)
	ds_read_b128 v[32:35], v186 offset:18432
	ds_read_b128 v[36:39], v186 offset:18464
	ds_read_b128 v[40:43], v186 offset:18496
	ds_read_b128 v[44:47], v186 offset:18528
	ds_read_b128 v[196:199], v186 offset:18560
	ds_read_b128 v[200:203], v186 offset:18592
	ds_read_b128 v[204:207], v186 offset:18624
	ds_read_b128 v[208:211], v186 offset:18656
	s_waitcnt lgkmcnt(7)
	v_mfma_f32_32x32x16_bf16 v[48:63], v[64:67], v[32:35], 0
	s_waitcnt lgkmcnt(6)
	v_mfma_f32_32x32x16_bf16 v[48:63], v[68:71], v[36:39], v[48:63]
	s_waitcnt lgkmcnt(5)
	v_mfma_f32_32x32x16_bf16 v[48:63], v[72:75], v[40:43], v[48:63]
	s_waitcnt lgkmcnt(4)
	v_mfma_f32_32x32x16_bf16 v[48:63], v[76:79], v[44:47], v[48:63]
	s_waitcnt lgkmcnt(3)
	v_mfma_f32_32x32x16_bf16 v[48:63], v[84:87], v[196:199], v[48:63]
	s_waitcnt lgkmcnt(2)
	v_mfma_f32_32x32x16_bf16 v[48:63], v[88:91], v[200:203], v[48:63]
	s_waitcnt lgkmcnt(1)
	v_mfma_f32_32x32x16_bf16 v[48:63], v[96:99], v[204:207], v[48:63]
	s_waitcnt lgkmcnt(0)
	v_mfma_f32_32x32x16_bf16 v[48:63], v[108:111], v[208:211], v[48:63]
	s_add_i32 s2, s2, 32
	v_add_u32_e32 v187, 4, v187
	s_waitcnt vmcnt(3)
	v_mfma_f32_32x32x16_bf16 v[0:15], v[238:241], v[104:107], 0
	v_mfma_f32_32x32x16_bf16 v[16:31], v[238:241], v[116:119], 0
	v_mfma_f32_32x32x16_bf16 v[32:47], v[238:241], v[92:95], 0
	v_mfma_f32_32x32x16_bf16 v[196:211], v[238:241], v[112:115], 0
	s_and_b32 s18, s16, 0x2000
	s_and_b32 s17, s2, 0x1f00
	s_or_b32 s17, s17, s13
	s_lshl_b32 s17, s17, 12
	s_and_b32 s17, s17, 0x1ffc000
	s_addk_i32 s16, 0x800
	v_add_u32_e32 v222, s2, v174
	v_and_or_b32 v223, v187, 14, s4
	v_lshlrev_b32_e32 v225, 5, v222
	v_lshlrev_b32_e32 v226, 1, v222
	v_lshl_or_b32 v227, v223, 9, s18
	v_and_b32_e32 v222, 0x1e0, v225
	v_and_b32_e32 v223, 16, v226
	v_or_b32_e32 v224, v222, v132
	v_bitop3_b32 v222, v222, v223, v132 bitop3:0x36
	v_or_b32_e32 v225, s17, v227
	v_bitop3_b32 v226, v224, v223, 8 bitop3:0x36
	v_or_b32_e32 v227, v222, v225
	v_fmac_f32_e32 v48, v100, v228
	v_fmac_f32_e32 v49, v101, v229
	v_fmac_f32_e32 v50, v102, v230
	v_fmac_f32_e32 v51, v103, v231
	v_fmac_f32_e32 v52, v80, v232
	v_fmac_f32_e32 v53, v81, v233
	v_fmac_f32_e32 v54, v82, v234
	v_fmac_f32_e32 v55, v83, v235
	v_mul_f32_e32 v56, v48, v48
	v_mul_f32_e32 v57, v49, v49
	v_mul_f32_e32 v58, v50, v50
	v_mul_f32_e32 v59, v51, v51
	v_mul_f32_e32 v60, v52, v52
	v_mul_f32_e32 v61, v53, v53
	v_mul_f32_e32 v62, v54, v54
	v_mul_f32_e32 v63, v55, v55
	v_fmaak_f32 v56, v56, v246, 0xc0135761
	v_fmaak_f32 v57, v57, v246, 0xc0135761
	v_fmaak_f32 v58, v58, v246, 0xc0135761
	v_fmaak_f32 v59, v59, v246, 0xc0135761
	v_fmaak_f32 v60, v60, v246, 0xc0135761
	v_fmaak_f32 v61, v61, v246, 0xc0135761
	v_fmaak_f32 v62, v62, v246, 0xc0135761
	v_fmaak_f32 v63, v63, v246, 0xc0135761
	v_mul_f32_e32 v56, v48, v56
	v_mul_f32_e32 v57, v49, v57
	v_mul_f32_e32 v58, v50, v58
	v_mul_f32_e32 v59, v51, v59
	v_mul_f32_e32 v60, v52, v60
	v_mul_f32_e32 v61, v53, v61
	v_mul_f32_e32 v62, v54, v62
	v_mul_f32_e32 v63, v55, v63
	v_exp_f32_e32 v56, v56
	v_exp_f32_e32 v57, v57
	v_exp_f32_e32 v58, v58
	v_exp_f32_e32 v59, v59
	v_exp_f32_e32 v60, v60
	v_exp_f32_e32 v61, v61
	v_exp_f32_e32 v62, v62
	v_exp_f32_e32 v63, v63
	v_add_f32_e32 v56, 1.0, v56
	v_add_f32_e32 v57, 1.0, v57
	v_add_f32_e32 v58, 1.0, v58
	v_add_f32_e32 v59, 1.0, v59
	v_add_f32_e32 v60, 1.0, v60
	v_add_f32_e32 v61, 1.0, v61
	v_add_f32_e32 v62, 1.0, v62
	v_add_f32_e32 v63, 1.0, v63
	v_rcp_f32_e32 v56, v56
	v_rcp_f32_e32 v57, v57
	v_rcp_f32_e32 v58, v58
	v_rcp_f32_e32 v59, v59
	v_rcp_f32_e32 v60, v60
	v_rcp_f32_e32 v61, v61
	v_rcp_f32_e32 v62, v62
	v_rcp_f32_e32 v63, v63
	v_mul_f32_e32 v48, v48, v56
	v_mul_f32_e32 v49, v49, v57
	v_mul_f32_e32 v50, v50, v58
	v_mul_f32_e32 v51, v51, v59
	v_mul_f32_e32 v52, v52, v60
	v_mul_f32_e32 v53, v53, v61
	v_mul_f32_e32 v54, v54, v62
	v_mul_f32_e32 v55, v55, v63
	v_cvt_pk_bf16_f32 v56, v48, v49
	v_cvt_pk_bf16_f32 v57, v50, v51
	v_cvt_pk_bf16_f32 v58, v52, v53
	v_cvt_pk_bf16_f32 v59, v54, v55
	global_store_dwordx2 v236, v[56:57], s[90:91]
	global_store_dwordx2 v237, v[58:59], s[90:91]
	v_lshlrev_b32_e32 v228, 16, v242
	v_and_b32_e32 v229, 0xffff0000, v242
	v_lshlrev_b32_e32 v230, 16, v243
	v_and_b32_e32 v231, 0xffff0000, v243
	v_lshlrev_b32_e32 v232, 16, v244
	v_and_b32_e32 v233, 0xffff0000, v244
	v_lshlrev_b32_e32 v234, 16, v245
	v_and_b32_e32 v235, 0xffff0000, v245
	v_or_b32_e32 v237, v226, v225
	v_lshlrev_b32_e32 v236, 1, v227
	v_lshlrev_b32_e32 v237, 1, v237
	s_add_u32 s0, s0, 0x40000
	s_addc_u32 s1, s1, 0
	v_lshl_add_u64 v[216:217], v[152:153], 0, s[0:1]
	v_lshl_add_u64 v[218:219], v[154:155], 0, s[0:1]
	v_lshl_add_u64 v[220:221], v[150:151], 0, s[0:1]
	global_load_dwordx4 v[238:241], v[216:217], off
	global_load_dwordx2 v[242:243], v[218:219], off
	global_load_dwordx2 v[244:245], v[220:221], off
	v_permlane32_swap_b32_e32 v0, v16
	v_permlane32_swap_b32_e32 v1, v17
	v_permlane32_swap_b32_e32 v2, v18
	v_permlane32_swap_b32_e32 v3, v19
	v_permlane32_swap_b32_e32 v4, v20
	v_permlane32_swap_b32_e32 v5, v21
	v_permlane32_swap_b32_e32 v6, v22
	v_permlane32_swap_b32_e32 v7, v23
	v_permlane32_swap_b32_e32 v8, v24
	v_permlane32_swap_b32_e32 v9, v25
	v_permlane32_swap_b32_e32 v10, v26
	v_permlane32_swap_b32_e32 v11, v27
	v_permlane32_swap_b32_e32 v12, v28
	v_permlane32_swap_b32_e32 v13, v29
	v_permlane32_swap_b32_e32 v14, v30
	v_permlane32_swap_b32_e32 v15, v31
	v_permlane32_swap_b32_e32 v32, v196
	v_permlane32_swap_b32_e32 v33, v197
	v_permlane32_swap_b32_e32 v34, v198
	v_permlane32_swap_b32_e32 v35, v199
	v_permlane32_swap_b32_e32 v36, v200
	v_permlane32_swap_b32_e32 v37, v201
	v_permlane32_swap_b32_e32 v38, v202
	v_permlane32_swap_b32_e32 v39, v203
	v_permlane32_swap_b32_e32 v40, v204
	v_permlane32_swap_b32_e32 v41, v205
	v_permlane32_swap_b32_e32 v42, v206
	v_permlane32_swap_b32_e32 v43, v207
	v_permlane32_swap_b32_e32 v44, v208
	v_permlane32_swap_b32_e32 v45, v209
	v_permlane32_swap_b32_e32 v46, v210
	v_permlane32_swap_b32_e32 v47, v211
	v_fmac_f32_e32 v0, v160, v188
	v_fmac_f32_e32 v32, v160, v189
	v_fma_f32 v0, -v161, v189, v0
	v_fmac_f32_e32 v32, v161, v188
	v_fmac_f32_e32 v1, v160, v0
	v_fmac_f32_e32 v33, v160, v32
	v_cvt_pk_bf16_f32 v212, v0, v32
	v_fma_f32 v1, -v161, v32, v1
	v_fmac_f32_e32 v33, v161, v0
	ds_write_b32 v185, v212 offset:18432
	v_fmac_f32_e32 v2, v160, v1
	v_fmac_f32_e32 v34, v160, v33
	v_cvt_pk_bf16_f32 v213, v1, v33
	v_fma_f32 v2, -v161, v33, v2
	v_fmac_f32_e32 v34, v161, v1
	ds_write_b32 v185, v213 offset:18704
	v_fmac_f32_e32 v3, v160, v2
	v_fmac_f32_e32 v35, v160, v34
	v_cvt_pk_bf16_f32 v214, v2, v34
	v_fma_f32 v3, -v161, v34, v3
	v_fmac_f32_e32 v35, v161, v2
	ds_write_b32 v185, v214 offset:18976
	v_fmac_f32_e32 v16, v160, v3
	v_fmac_f32_e32 v196, v160, v35
	v_cvt_pk_bf16_f32 v215, v3, v35
	v_fma_f32 v16, -v161, v35, v16
	v_fmac_f32_e32 v196, v161, v3
	ds_write_b32 v185, v215 offset:19248
	v_fmac_f32_e32 v17, v160, v16
	v_fmac_f32_e32 v197, v160, v196
	v_cvt_pk_bf16_f32 v212, v16, v196
	v_fma_f32 v17, -v161, v196, v17
	v_fmac_f32_e32 v197, v161, v16
	ds_write_b32 v185, v212 offset:19520
	v_fmac_f32_e32 v18, v160, v17
	v_fmac_f32_e32 v198, v160, v197
	v_cvt_pk_bf16_f32 v213, v17, v197
	v_fma_f32 v18, -v161, v197, v18
	v_fmac_f32_e32 v198, v161, v17
	ds_write_b32 v185, v213 offset:19792
	v_fmac_f32_e32 v19, v160, v18
	v_fmac_f32_e32 v199, v160, v198
	v_cvt_pk_bf16_f32 v214, v18, v198
	v_fma_f32 v19, -v161, v198, v19
	v_fmac_f32_e32 v199, v161, v18
	ds_write_b32 v185, v214 offset:20064
	v_fmac_f32_e32 v4, v160, v19
	v_fmac_f32_e32 v36, v160, v199
	v_cvt_pk_bf16_f32 v215, v19, v199
	v_fma_f32 v4, -v161, v199, v4
	v_fmac_f32_e32 v36, v161, v19
	ds_write_b32 v185, v215 offset:20336
	v_fmac_f32_e32 v5, v160, v4
	v_fmac_f32_e32 v37, v160, v36
	v_cvt_pk_bf16_f32 v212, v4, v36
	v_fma_f32 v5, -v161, v36, v5
	v_fmac_f32_e32 v37, v161, v4
	ds_write_b32 v185, v212 offset:20608
	v_fmac_f32_e32 v6, v160, v5
	v_fmac_f32_e32 v38, v160, v37
	v_cvt_pk_bf16_f32 v213, v5, v37
	v_fma_f32 v6, -v161, v37, v6
	v_fmac_f32_e32 v38, v161, v5
	ds_write_b32 v185, v213 offset:20880
	v_fmac_f32_e32 v7, v160, v6
	v_fmac_f32_e32 v39, v160, v38
	v_cvt_pk_bf16_f32 v214, v6, v38
	v_fma_f32 v7, -v161, v38, v7
	v_fmac_f32_e32 v39, v161, v6
	ds_write_b32 v185, v214 offset:21152
	v_fmac_f32_e32 v20, v160, v7
	v_fmac_f32_e32 v200, v160, v39
	v_cvt_pk_bf16_f32 v215, v7, v39
	v_fma_f32 v20, -v161, v39, v20
	v_fmac_f32_e32 v200, v161, v7
	ds_write_b32 v185, v215 offset:21424
	v_fmac_f32_e32 v21, v160, v20
	v_fmac_f32_e32 v201, v160, v200
	v_cvt_pk_bf16_f32 v212, v20, v200
	v_fma_f32 v21, -v161, v200, v21
	v_fmac_f32_e32 v201, v161, v20
	ds_write_b32 v185, v212 offset:21696
	v_fmac_f32_e32 v22, v160, v21
	v_fmac_f32_e32 v202, v160, v201
	v_cvt_pk_bf16_f32 v213, v21, v201
	v_fma_f32 v22, -v161, v201, v22
	v_fmac_f32_e32 v202, v161, v21
	ds_write_b32 v185, v213 offset:21968
	v_fmac_f32_e32 v23, v160, v22
	v_fmac_f32_e32 v203, v160, v202
	v_cvt_pk_bf16_f32 v214, v22, v202
	v_fma_f32 v23, -v161, v202, v23
	v_fmac_f32_e32 v203, v161, v22
	ds_write_b32 v185, v214 offset:22240
	v_fmac_f32_e32 v8, v160, v23
	v_fmac_f32_e32 v40, v160, v203
	v_cvt_pk_bf16_f32 v215, v23, v203
	v_fma_f32 v8, -v161, v203, v8
	v_fmac_f32_e32 v40, v161, v23
	ds_write_b32 v185, v215 offset:22512
	v_fmac_f32_e32 v9, v160, v8
	v_fmac_f32_e32 v41, v160, v40
	v_cvt_pk_bf16_f32 v212, v8, v40
	v_fma_f32 v9, -v161, v40, v9
	v_fmac_f32_e32 v41, v161, v8
	ds_write_b32 v185, v212 offset:22784
	v_fmac_f32_e32 v10, v160, v9
	v_fmac_f32_e32 v42, v160, v41
	v_cvt_pk_bf16_f32 v213, v9, v41
	v_fma_f32 v10, -v161, v41, v10
	v_fmac_f32_e32 v42, v161, v9
	ds_write_b32 v185, v213 offset:23056
	v_fmac_f32_e32 v11, v160, v10
	v_fmac_f32_e32 v43, v160, v42
	v_cvt_pk_bf16_f32 v214, v10, v42
	v_fma_f32 v11, -v161, v42, v11
	v_fmac_f32_e32 v43, v161, v10
	ds_write_b32 v185, v214 offset:23328
	v_fmac_f32_e32 v24, v160, v11
	v_fmac_f32_e32 v204, v160, v43
	v_cvt_pk_bf16_f32 v215, v11, v43
	v_fma_f32 v24, -v161, v43, v24
	v_fmac_f32_e32 v204, v161, v11
	ds_write_b32 v185, v215 offset:23600
	v_fmac_f32_e32 v25, v160, v24
	v_fmac_f32_e32 v205, v160, v204
	v_cvt_pk_bf16_f32 v212, v24, v204
	v_fma_f32 v25, -v161, v204, v25
	v_fmac_f32_e32 v205, v161, v24
	ds_write_b32 v185, v212 offset:23872
	v_fmac_f32_e32 v26, v160, v25
	v_fmac_f32_e32 v206, v160, v205
	v_cvt_pk_bf16_f32 v213, v25, v205
	v_fma_f32 v26, -v161, v205, v26
	v_fmac_f32_e32 v206, v161, v25
	ds_write_b32 v185, v213 offset:24144
	v_fmac_f32_e32 v27, v160, v26
	v_fmac_f32_e32 v207, v160, v206
	v_cvt_pk_bf16_f32 v214, v26, v206
	v_fma_f32 v27, -v161, v206, v27
	v_fmac_f32_e32 v207, v161, v26
	ds_write_b32 v185, v214 offset:24416
	v_fmac_f32_e32 v12, v160, v27
	v_fmac_f32_e32 v44, v160, v207
	v_cvt_pk_bf16_f32 v215, v27, v207
	v_fma_f32 v12, -v161, v207, v12
	v_fmac_f32_e32 v44, v161, v27
	ds_write_b32 v185, v215 offset:24688
	v_fmac_f32_e32 v13, v160, v12
	v_fmac_f32_e32 v45, v160, v44
	v_cvt_pk_bf16_f32 v212, v12, v44
	v_fma_f32 v13, -v161, v44, v13
	v_fmac_f32_e32 v45, v161, v12
	ds_write_b32 v185, v212 offset:24960
	v_fmac_f32_e32 v14, v160, v13
	v_fmac_f32_e32 v46, v160, v45
	v_cvt_pk_bf16_f32 v213, v13, v45
	v_fma_f32 v14, -v161, v45, v14
	v_fmac_f32_e32 v46, v161, v13
	ds_write_b32 v185, v213 offset:25232
	v_fmac_f32_e32 v15, v160, v14
	v_fmac_f32_e32 v47, v160, v46
	v_cvt_pk_bf16_f32 v214, v14, v46
	v_fma_f32 v15, -v161, v46, v15
	v_fmac_f32_e32 v47, v161, v14
	ds_write_b32 v185, v214 offset:25504
	v_fmac_f32_e32 v28, v160, v15
	v_fmac_f32_e32 v208, v160, v47
	v_cvt_pk_bf16_f32 v215, v15, v47
	v_fma_f32 v28, -v161, v47, v28
	v_fmac_f32_e32 v208, v161, v15
	ds_write_b32 v185, v215 offset:25776
	v_fmac_f32_e32 v29, v160, v28
	v_fmac_f32_e32 v209, v160, v208
	v_cvt_pk_bf16_f32 v212, v28, v208
	v_fma_f32 v29, -v161, v208, v29
	v_fmac_f32_e32 v209, v161, v28
	ds_write_b32 v185, v212 offset:26048
	v_fmac_f32_e32 v30, v160, v29
	v_fmac_f32_e32 v210, v160, v209
	v_cvt_pk_bf16_f32 v213, v29, v209
	v_fma_f32 v30, -v161, v209, v30
	v_fmac_f32_e32 v210, v161, v29
	ds_write_b32 v185, v213 offset:26320
	v_fmac_f32_e32 v31, v160, v30
	v_fmac_f32_e32 v211, v160, v210
	v_cvt_pk_bf16_f32 v214, v30, v210
	v_fma_f32 v31, -v161, v210, v31
	v_fmac_f32_e32 v211, v161, v30
	ds_write_b32 v185, v214 offset:26592
	v_mov_b32_e32 v188, v31
	v_mov_b32_e32 v189, v211
	v_cvt_pk_bf16_f32 v215, v31, v211
	ds_write_b32 v185, v215 offset:26864
	s_waitcnt lgkmcnt(0)
	ds_read_b128 v[32:35], v186 offset:18432
	ds_read_b128 v[36:39], v186 offset:18464
	ds_read_b128 v[40:43], v186 offset:18496
	ds_read_b128 v[44:47], v186 offset:18528
	ds_read_b128 v[196:199], v186 offset:18560
	ds_read_b128 v[200:203], v186 offset:18592
	ds_read_b128 v[204:207], v186 offset:18624
	ds_read_b128 v[208:211], v186 offset:18656
	s_waitcnt lgkmcnt(7)
	v_mfma_f32_32x32x16_bf16 v[48:63], v[64:67], v[32:35], 0
	s_waitcnt lgkmcnt(6)
	v_mfma_f32_32x32x16_bf16 v[48:63], v[68:71], v[36:39], v[48:63]
	s_waitcnt lgkmcnt(5)
	v_mfma_f32_32x32x16_bf16 v[48:63], v[72:75], v[40:43], v[48:63]
	s_waitcnt lgkmcnt(4)
	v_mfma_f32_32x32x16_bf16 v[48:63], v[76:79], v[44:47], v[48:63]
	s_waitcnt lgkmcnt(3)
	v_mfma_f32_32x32x16_bf16 v[48:63], v[84:87], v[196:199], v[48:63]
	s_waitcnt lgkmcnt(2)
	v_mfma_f32_32x32x16_bf16 v[48:63], v[88:91], v[200:203], v[48:63]
	s_waitcnt lgkmcnt(1)
	v_mfma_f32_32x32x16_bf16 v[48:63], v[96:99], v[204:207], v[48:63]
	s_waitcnt lgkmcnt(0)
	v_mfma_f32_32x32x16_bf16 v[48:63], v[108:111], v[208:211], v[48:63]
	s_add_i32 s2, s2, 32
	v_add_u32_e32 v187, 4, v187
	s_cmp_eq_u32 s0, 0x1000000
	s_cbranch_scc0 .Lscan_tile
	s_nop 11
	v_fmac_f32_e32 v48, v100, v228
	v_fmac_f32_e32 v49, v101, v229
	v_fmac_f32_e32 v50, v102, v230
	v_fmac_f32_e32 v51, v103, v231
	v_fmac_f32_e32 v52, v80, v232
	v_fmac_f32_e32 v53, v81, v233
	v_fmac_f32_e32 v54, v82, v234
	v_fmac_f32_e32 v55, v83, v235
	v_mul_f32_e32 v56, v48, v48
	v_mul_f32_e32 v57, v49, v49
	v_mul_f32_e32 v58, v50, v50
	v_mul_f32_e32 v59, v51, v51
	v_mul_f32_e32 v60, v52, v52
	v_mul_f32_e32 v61, v53, v53
	v_mul_f32_e32 v62, v54, v54
	v_mul_f32_e32 v63, v55, v55
	v_fmaak_f32 v56, v56, v246, 0xc0135761
	v_fmaak_f32 v57, v57, v246, 0xc0135761
	v_fmaak_f32 v58, v58, v246, 0xc0135761
	v_fmaak_f32 v59, v59, v246, 0xc0135761
	v_fmaak_f32 v60, v60, v246, 0xc0135761
	v_fmaak_f32 v61, v61, v246, 0xc0135761
	v_fmaak_f32 v62, v62, v246, 0xc0135761
	v_fmaak_f32 v63, v63, v246, 0xc0135761
	v_mul_f32_e32 v56, v48, v56
	v_mul_f32_e32 v57, v49, v57
	v_mul_f32_e32 v58, v50, v58
	v_mul_f32_e32 v59, v51, v59
	v_mul_f32_e32 v60, v52, v60
	v_mul_f32_e32 v61, v53, v61
	v_mul_f32_e32 v62, v54, v62
	v_mul_f32_e32 v63, v55, v63
	v_exp_f32_e32 v56, v56
	v_exp_f32_e32 v57, v57
	v_exp_f32_e32 v58, v58
	v_exp_f32_e32 v59, v59
	v_exp_f32_e32 v60, v60
	v_exp_f32_e32 v61, v61
	v_exp_f32_e32 v62, v62
	v_exp_f32_e32 v63, v63
	v_add_f32_e32 v56, 1.0, v56
	v_add_f32_e32 v57, 1.0, v57
	v_add_f32_e32 v58, 1.0, v58
	v_add_f32_e32 v59, 1.0, v59
	v_add_f32_e32 v60, 1.0, v60
	v_add_f32_e32 v61, 1.0, v61
	v_add_f32_e32 v62, 1.0, v62
	v_add_f32_e32 v63, 1.0, v63
	v_rcp_f32_e32 v56, v56
	v_rcp_f32_e32 v57, v57
	v_rcp_f32_e32 v58, v58
	v_rcp_f32_e32 v59, v59
	v_rcp_f32_e32 v60, v60
	v_rcp_f32_e32 v61, v61
	v_rcp_f32_e32 v62, v62
	v_rcp_f32_e32 v63, v63
	v_mul_f32_e32 v48, v48, v56
	v_mul_f32_e32 v49, v49, v57
	v_mul_f32_e32 v50, v50, v58
	v_mul_f32_e32 v51, v51, v59
	v_mul_f32_e32 v52, v52, v60
	v_mul_f32_e32 v53, v53, v61
	v_mul_f32_e32 v54, v54, v62
	v_mul_f32_e32 v55, v55, v63
	v_cvt_pk_bf16_f32 v56, v48, v49
	v_cvt_pk_bf16_f32 v57, v50, v51
	v_cvt_pk_bf16_f32 v58, v52, v53
	v_cvt_pk_bf16_f32 v59, v54, v55
	global_store_dwordx2 v236, v[56:57], s[90:91]
	global_store_dwordx2 v237, v[58:59], s[90:91]
	s_add_i32 s6, s6, s7
	s_add_i32 s10, s10, s11
	s_add_i32 s12, s12, s7
	s_cmpk_gt_i32 s6, 0x3ff
	s_cbranch_scc0 .LBB0_563
